# baseline (speedup 1.0000x reference)
; #define LDA(dst, b, h) for (int m = 0; m < 4; ++m) for (int k = 0; k < 2; ++k) \
;     dst[m][k] = *reinterpret_cast<const bf16x8*>((char*)SA(b, h) + aoff + m * 2048 + k * 1024)
; #define LDB(dst, b, h) for (int n = 0; n < 2; ++n) for (int k = 0; k < 2; ++k) \
;     dst[n][k] = *reinterpret_cast<const bf16x8*>((char*)SB(b, h) + boff + n * 2048 + k * 1024)
; #define MMA(ai, bj, At, Bt) do { __builtin_amdgcn_s_setprio(1); \
;     for (int m = 0; m < 4; ++m) for (int n = 0; n < 2; ++n) for (int k = 0; k < 2; ++k) \
;       acc[ai][bj][m][n] = __builtin_amdgcn_mfma_f32_16x16x32_bf16(Bt[n][k], At[m][k], acc[ai][bj][m][n], 0, 0, 0); \
;     __builtin_amdgcn_s_setprio(0); } while (0)
; #define WAIT_V(n) asm volatile("s_waitcnt vmcnt(" #n ")" ::: "memory")
; #define WAIT_L(n) asm volatile("s_waitcnt lgkmcnt(" #n ")" ::: "memory")
; #define BAR __builtin_amdgcn_s_barrier()
; #define SCHED __builtin_amdgcn_sched_barrier(0)
; DEV void gemm_core(const u16* __restrict__ A, int lda, const u16* __restrict__ Bt, int ldb, int K,
;                    int brow, int bcol, f32x4 (&acc)[2][2][4][2]) {
;     ...
;     LDB(B0, 0, 0); SCHED; LDA(At, 0, 0); STAGE(SA(1, 1), A, lda, brow + HALF, t + 1);
;     WAIT_L(8); BAR; WAIT_L(0); MMA(0, 0, At, B0); BAR; SCHED;
;     LDB(B1, 0, 1); STAGE(SB(0, 0), Bt, ldb, bcol, t + 2);
;     BAR; WAIT_L(0); MMA(0, 1, At, B1); BAR;
;     LDA(At, 0, 1); STAGE(SA(0, 0), A, lda, brow, t + 2);
;     BAR; WAIT_L(0); MMA(1, 0, At, B0); BAR; SCHED;
;     STAGE(SB(0, 1), Bt, ldb, bcol + HALF, t + 2);
;     WAIT_V(6); BAR; MMA(1, 1, At, B1); BAR;
.LBB0_191:
	global_load_lds_dwordx4 v153, s[6:7]
	s_add_i32 m0, s38, 0xe000
	ds_read_b128 v[162:165], v199
	global_load_lds_dwordx4 v152, s[6:7]
	ds_read_b128 v[166:169], v199 offset:1024
	ds_read_b128 v[170:173], v199 offset:2048
	ds_read_b128 v[174:177], v199 offset:3072
	ds_read_b128 v[200:203], v197
	ds_read_b128 v[204:207], v197 offset:1024
	ds_read_b128 v[208:211], v197 offset:2048
	ds_read_b128 v[212:215], v197 offset:3072
	ds_read_b128 v[216:219], v197 offset:4096
	ds_read_b128 v[220:223], v197 offset:5120
	ds_read_b128 v[224:227], v197 offset:6144
	ds_read_b128 v[228:231], v197 offset:7168
	s_waitcnt lgkmcnt(8)
	s_barrier
	s_waitcnt lgkmcnt(0)
	v_mfma_f32_16x16x32_bf16 v[0:3], v[162:165], v[200:203], v[0:3]
	v_mfma_f32_16x16x32_bf16 v[126:129], v[170:173], v[200:203], v[126:129]
	v_mfma_f32_16x16x32_bf16 v[122:125], v[162:165], v[208:211], v[122:125]
	v_mfma_f32_16x16x32_bf16 v[118:121], v[170:173], v[208:211], v[118:121]
	v_mfma_f32_16x16x32_bf16 v[114:117], v[162:165], v[216:219], v[114:117]
	v_mfma_f32_16x16x32_bf16 v[110:113], v[170:173], v[216:219], v[110:113]
	v_mfma_f32_16x16x32_bf16 v[106:109], v[162:165], v[224:227], v[106:109]
	v_mfma_f32_16x16x32_bf16 v[102:105], v[170:173], v[224:227], v[102:105]
	v_mfma_f32_16x16x32_bf16 v[0:3], v[166:169], v[204:207], v[0:3]
	v_mfma_f32_16x16x32_bf16 v[126:129], v[174:177], v[204:207], v[126:129]
	v_mfma_f32_16x16x32_bf16 v[122:125], v[166:169], v[212:215], v[122:125]
	v_mfma_f32_16x16x32_bf16 v[118:121], v[174:177], v[212:215], v[118:121]
	v_mfma_f32_16x16x32_bf16 v[114:117], v[166:169], v[220:223], v[114:117]
	v_mfma_f32_16x16x32_bf16 v[110:113], v[174:177], v[220:223], v[110:113]
	v_mfma_f32_16x16x32_bf16 v[106:109], v[166:169], v[228:231], v[106:109]
	v_mfma_f32_16x16x32_bf16 v[102:105], v[174:177], v[228:231], v[102:105]
	v_add_u32_e32 v153, 0x80, v153
	v_add_u32_e32 v152, 0x80, v152
	s_add_i32 m0, s38, 0x10000
	s_barrier
	global_load_lds_dwordx4 v159, s[8:9]
	s_add_i32 m0, s38, 0x12000
	ds_read_b128 v[232:235], v250
	global_load_lds_dwordx4 v158, s[8:9]
	ds_read_b128 v[236:239], v250 offset:1024
	ds_read_b128 v[240:243], v250 offset:2048
	ds_read_b128 v[244:247], v250 offset:3072
	s_add_i32 s36, s36, 2
	s_barrier
	s_waitcnt lgkmcnt(0)
	v_mfma_f32_16x16x32_bf16 v[98:101], v[232:235], v[200:203], v[98:101]
	v_mfma_f32_16x16x32_bf16 v[94:97], v[240:243], v[200:203], v[94:97]
	v_mfma_f32_16x16x32_bf16 v[90:93], v[232:235], v[208:211], v[90:93]
	v_mfma_f32_16x16x32_bf16 v[86:89], v[240:243], v[208:211], v[86:89]
	v_mfma_f32_16x16x32_bf16 v[82:85], v[232:235], v[216:219], v[82:85]
	v_mfma_f32_16x16x32_bf16 v[78:81], v[240:243], v[216:219], v[78:81]
	v_mfma_f32_16x16x32_bf16 v[74:77], v[232:235], v[224:227], v[74:77]
	v_mfma_f32_16x16x32_bf16 v[70:73], v[240:243], v[224:227], v[70:73]
	v_mfma_f32_16x16x32_bf16 v[98:101], v[236:239], v[204:207], v[98:101]
	v_mfma_f32_16x16x32_bf16 v[94:97], v[244:247], v[204:207], v[94:97]
	v_mfma_f32_16x16x32_bf16 v[90:93], v[236:239], v[212:215], v[90:93]
	v_mfma_f32_16x16x32_bf16 v[86:89], v[244:247], v[212:215], v[86:89]
	v_mfma_f32_16x16x32_bf16 v[82:85], v[236:239], v[220:223], v[82:85]
	v_mfma_f32_16x16x32_bf16 v[78:81], v[244:247], v[220:223], v[78:81]
	v_mfma_f32_16x16x32_bf16 v[74:77], v[236:239], v[228:231], v[74:77]
	v_mfma_f32_16x16x32_bf16 v[70:73], v[244:247], v[228:231], v[70:73]
	v_add_u32_e32 v159, 0x80, v159
	v_add_u32_e32 v158, 0x80, v158
	s_mov_b32 m0, s38
	s_barrier
	global_load_lds_dwordx4 v157, s[6:7]
	s_add_i32 m0, s38, 0x2000
	ds_read_b128 v[200:203], v197 offset:16384
	global_load_lds_dwordx4 v156, s[6:7]
	ds_read_b128 v[204:207], v197 offset:17408
	ds_read_b128 v[208:211], v197 offset:18432
	ds_read_b128 v[212:215], v197 offset:19456
	ds_read_b128 v[216:219], v197 offset:20480
	ds_read_b128 v[220:223], v197 offset:21504
	ds_read_b128 v[224:227], v197 offset:22528
	ds_read_b128 v[228:231], v197 offset:23552
	s_barrier
	s_waitcnt lgkmcnt(0)
	v_mfma_f32_16x16x32_bf16 v[66:69], v[162:165], v[200:203], v[66:69]
	v_mfma_f32_16x16x32_bf16 v[62:65], v[170:173], v[200:203], v[62:65]
	v_mfma_f32_16x16x32_bf16 v[58:61], v[162:165], v[208:211], v[58:61]
	v_mfma_f32_16x16x32_bf16 v[54:57], v[170:173], v[208:211], v[54:57]
	v_mfma_f32_16x16x32_bf16 v[50:53], v[162:165], v[216:219], v[50:53]
	v_mfma_f32_16x16x32_bf16 v[46:49], v[170:173], v[216:219], v[46:49]
	v_mfma_f32_16x16x32_bf16 v[42:45], v[162:165], v[224:227], v[42:45]
	v_mfma_f32_16x16x32_bf16 v[38:41], v[170:173], v[224:227], v[38:41]
	v_mfma_f32_16x16x32_bf16 v[66:69], v[166:169], v[204:207], v[66:69]
	v_mfma_f32_16x16x32_bf16 v[62:65], v[174:177], v[204:207], v[62:65]
	v_mfma_f32_16x16x32_bf16 v[58:61], v[166:169], v[212:215], v[58:61]
	v_mfma_f32_16x16x32_bf16 v[54:57], v[174:177], v[212:215], v[54:57]
	v_mfma_f32_16x16x32_bf16 v[50:53], v[166:169], v[220:223], v[50:53]
	v_mfma_f32_16x16x32_bf16 v[46:49], v[174:177], v[220:223], v[46:49]
	v_mfma_f32_16x16x32_bf16 v[42:45], v[166:169], v[228:231], v[42:45]
	v_mfma_f32_16x16x32_bf16 v[38:41], v[174:177], v[228:231], v[38:41]
	v_add_u32_e32 v157, 0x80, v157
	v_add_u32_e32 v156, 0x80, v156
	s_add_i32 m0, s38, 0x14000
	s_barrier
	global_load_lds_dwordx4 v155, s[8:9]
	s_add_i32 m0, s38, 0x16000
	s_nop 0
	global_load_lds_dwordx4 v154, s[8:9]
	s_waitcnt vmcnt(6)
	s_barrier
; #define LDA(dst, b, h) for (int m = 0; m < 4; ++m) for (int k = 0; k < 2; ++k) \
;     dst[m][k] = *reinterpret_cast<const bf16x8*>((char*)SA(b, h) + aoff + m * 2048 + k * 1024)
; #define LDB(dst, b, h) for (int n = 0; n < 2; ++n) for (int k = 0; k < 2; ++k) \
;     dst[n][k] = *reinterpret_cast<const bf16x8*>((char*)SB(b, h) + boff + n * 2048 + k * 1024)
; #define MMA(ai, bj, At, Bt) do { __builtin_amdgcn_s_setprio(1); \
;     for (int m = 0; m < 4; ++m) for (int n = 0; n < 2; ++n) for (int k = 0; k < 2; ++k) \
;       acc[ai][bj][m][n] = __builtin_amdgcn_mfma_f32_16x16x32_bf16(Bt[n][k], At[m][k], acc[ai][bj][m][n], 0, 0, 0); \
;     __builtin_amdgcn_s_setprio(0); } while (0)
; #define WAIT_V(n) asm volatile("s_waitcnt vmcnt(" #n ")" ::: "memory")
; #define WAIT_L(n) asm volatile("s_waitcnt lgkmcnt(" #n ")" ::: "memory")
; #define BAR __builtin_amdgcn_s_barrier()
; #define SCHED __builtin_amdgcn_sched_barrier(0)
; DEV void gemm_core(const u16* __restrict__ A, int lda, const u16* __restrict__ Bt, int ldb, int K,
;                    int brow, int bcol, f32x4 (&acc)[2][2][4][2]) {
;     ...
;     WAIT_V(6); BAR; MMA(1, 1, At, B1); BAR;
;     LDB(B0, 1, 0); SCHED; LDA(At, 1, 0); STAGE(SA(0, 1), A, lda, brow + HALF, t + 2);
;     WAIT_L(8); BAR; WAIT_L(0); MMA(0, 0, At, B0); BAR; SCHED;
;     LDB(B1, 1, 1); STAGE(SB(1, 0), Bt, ldb, bcol, t + 3);
;     BAR; WAIT_L(0); MMA(0, 1, At, B1); BAR;
;     LDA(At, 1, 1); STAGE(SA(1, 0), A, lda, brow, t + 3);
	v_mfma_f32_16x16x32_bf16 v[34:37], v[232:235], v[200:203], v[34:37]
	v_mfma_f32_16x16x32_bf16 v[30:33], v[240:243], v[200:203], v[30:33]
	v_mfma_f32_16x16x32_bf16 v[26:29], v[232:235], v[208:211], v[26:29]
	v_mfma_f32_16x16x32_bf16 v[22:25], v[240:243], v[208:211], v[22:25]
	v_mfma_f32_16x16x32_bf16 v[18:21], v[232:235], v[216:219], v[18:21]
	v_mfma_f32_16x16x32_bf16 v[14:17], v[240:243], v[216:219], v[14:17]
	v_mfma_f32_16x16x32_bf16 v[10:13], v[232:235], v[224:227], v[10:13]
	v_mfma_f32_16x16x32_bf16 v[6:9], v[240:243], v[224:227], v[6:9]
	v_mfma_f32_16x16x32_bf16 v[34:37], v[236:239], v[204:207], v[34:37]
	v_mfma_f32_16x16x32_bf16 v[30:33], v[244:247], v[204:207], v[30:33]
	v_mfma_f32_16x16x32_bf16 v[26:29], v[236:239], v[212:215], v[26:29]
	v_mfma_f32_16x16x32_bf16 v[22:25], v[244:247], v[212:215], v[22:25]
	v_mfma_f32_16x16x32_bf16 v[18:21], v[236:239], v[220:223], v[18:21]
	v_mfma_f32_16x16x32_bf16 v[14:17], v[244:247], v[220:223], v[14:17]
	v_mfma_f32_16x16x32_bf16 v[10:13], v[236:239], v[228:231], v[10:13]
	v_mfma_f32_16x16x32_bf16 v[6:9], v[244:247], v[228:231], v[6:9]
	v_add_u32_e32 v155, 0x80, v155
	v_add_u32_e32 v154, 0x80, v154
	s_add_i32 m0, s38, 0x4000
	s_barrier
	global_load_lds_dwordx4 v153, s[6:7]
	s_add_i32 m0, s38, 0x6000
	ds_read_b128 v[162:165], v251
	global_load_lds_dwordx4 v152, s[6:7]
	ds_read_b128 v[166:169], v251 offset:1024
	ds_read_b128 v[170:173], v251 offset:2048
	ds_read_b128 v[174:177], v251 offset:3072
	ds_read_b128 v[200:203], v197 offset:32768
	ds_read_b128 v[204:207], v197 offset:33792
	ds_read_b128 v[208:211], v197 offset:34816
	ds_read_b128 v[212:215], v197 offset:35840
	ds_read_b128 v[216:219], v197 offset:36864
	ds_read_b128 v[220:223], v197 offset:37888
	ds_read_b128 v[224:227], v197 offset:38912
	ds_read_b128 v[228:231], v197 offset:39936
	s_waitcnt lgkmcnt(8)
	s_barrier
	s_waitcnt lgkmcnt(0)
	v_mfma_f32_16x16x32_bf16 v[0:3], v[162:165], v[200:203], v[0:3]
	v_mfma_f32_16x16x32_bf16 v[126:129], v[170:173], v[200:203], v[126:129]
	v_mfma_f32_16x16x32_bf16 v[122:125], v[162:165], v[208:211], v[122:125]
	v_mfma_f32_16x16x32_bf16 v[118:121], v[170:173], v[208:211], v[118:121]
	v_mfma_f32_16x16x32_bf16 v[114:117], v[162:165], v[216:219], v[114:117]
	v_mfma_f32_16x16x32_bf16 v[110:113], v[170:173], v[216:219], v[110:113]
	v_mfma_f32_16x16x32_bf16 v[106:109], v[162:165], v[224:227], v[106:109]
	v_mfma_f32_16x16x32_bf16 v[102:105], v[170:173], v[224:227], v[102:105]
	v_mfma_f32_16x16x32_bf16 v[0:3], v[166:169], v[204:207], v[0:3]
	v_mfma_f32_16x16x32_bf16 v[126:129], v[174:177], v[204:207], v[126:129]
	v_mfma_f32_16x16x32_bf16 v[122:125], v[166:169], v[212:215], v[122:125]
	v_mfma_f32_16x16x32_bf16 v[118:121], v[174:177], v[212:215], v[118:121]
	v_mfma_f32_16x16x32_bf16 v[114:117], v[166:169], v[220:223], v[114:117]
	v_mfma_f32_16x16x32_bf16 v[110:113], v[174:177], v[220:223], v[110:113]
	v_mfma_f32_16x16x32_bf16 v[106:109], v[166:169], v[228:231], v[106:109]
	v_mfma_f32_16x16x32_bf16 v[102:105], v[174:177], v[228:231], v[102:105]
	v_add_u32_e32 v153, 0x80, v153
	v_add_u32_e32 v152, 0x80, v152
	s_add_i32 m0, s38, 0x18000
	s_barrier
	global_load_lds_dwordx4 v159, s[8:9]
	s_add_i32 m0, s38, 0x1a000
	ds_read_b128 v[232:235], v252
	global_load_lds_dwordx4 v158, s[8:9]
	ds_read_b128 v[236:239], v252 offset:1024
	ds_read_b128 v[240:243], v252 offset:2048
	ds_read_b128 v[244:247], v252 offset:3072
	s_barrier
	s_waitcnt lgkmcnt(0)
	v_mfma_f32_16x16x32_bf16 v[98:101], v[232:235], v[200:203], v[98:101]
	v_mfma_f32_16x16x32_bf16 v[94:97], v[240:243], v[200:203], v[94:97]
	v_mfma_f32_16x16x32_bf16 v[90:93], v[232:235], v[208:211], v[90:93]
	v_mfma_f32_16x16x32_bf16 v[86:89], v[240:243], v[208:211], v[86:89]
	v_mfma_f32_16x16x32_bf16 v[82:85], v[232:235], v[216:219], v[82:85]
	v_mfma_f32_16x16x32_bf16 v[78:81], v[240:243], v[216:219], v[78:81]
	v_mfma_f32_16x16x32_bf16 v[74:77], v[232:235], v[224:227], v[74:77]
	v_mfma_f32_16x16x32_bf16 v[70:73], v[240:243], v[224:227], v[70:73]
	v_mfma_f32_16x16x32_bf16 v[98:101], v[236:239], v[204:207], v[98:101]
	v_mfma_f32_16x16x32_bf16 v[94:97], v[244:247], v[204:207], v[94:97]
	v_mfma_f32_16x16x32_bf16 v[90:93], v[236:239], v[212:215], v[90:93]
	v_mfma_f32_16x16x32_bf16 v[86:89], v[244:247], v[212:215], v[86:89]
	v_mfma_f32_16x16x32_bf16 v[82:85], v[236:239], v[220:223], v[82:85]
	v_mfma_f32_16x16x32_bf16 v[78:81], v[244:247], v[220:223], v[78:81]
	v_mfma_f32_16x16x32_bf16 v[74:77], v[236:239], v[228:231], v[74:77]
	v_mfma_f32_16x16x32_bf16 v[70:73], v[244:247], v[228:231], v[70:73]
	v_add_u32_e32 v159, 0x80, v159
	v_add_u32_e32 v158, 0x80, v158
	s_add_i32 m0, s38, 0x8000
	s_barrier
	global_load_lds_dwordx4 v157, s[6:7]
	s_add_i32 m0, s38, 0xa000
	ds_read_b128 v[200:203], v197 offset:49152
	global_load_lds_dwordx4 v156, s[6:7]
	ds_read_b128 v[204:207], v197 offset:50176
	ds_read_b128 v[208:211], v197 offset:51200
	ds_read_b128 v[212:215], v197 offset:52224
	ds_read_b128 v[216:219], v197 offset:53248
	ds_read_b128 v[220:223], v197 offset:54272
	ds_read_b128 v[224:227], v197 offset:55296
	ds_read_b128 v[228:231], v197 offset:56320
	s_barrier
; #define LDA(dst, b, h) for (int m = 0; m < 4; ++m) for (int k = 0; k < 2; ++k) \
;     dst[m][k] = *reinterpret_cast<const bf16x8*>((char*)SA(b, h) + aoff + m * 2048 + k * 1024)
; #define LDB(dst, b, h) for (int n = 0; n < 2; ++n) for (int k = 0; k < 2; ++k) \
;     dst[n][k] = *reinterpret_cast<const bf16x8*>((char*)SB(b, h) + boff + n * 2048 + k * 1024)
; #define MMA(ai, bj, At, Bt) do { __builtin_amdgcn_s_setprio(1); \
;     for (int m = 0; m < 4; ++m) for (int n = 0; n < 2; ++n) for (int k = 0; k < 2; ++k) \
;       acc[ai][bj][m][n] = __builtin_amdgcn_mfma_f32_16x16x32_bf16(Bt[n][k], At[m][k], acc[ai][bj][m][n], 0, 0, 0); \
;     __builtin_amdgcn_s_setprio(0); } while (0)
; #define WAIT_V(n) asm volatile("s_waitcnt vmcnt(" #n ")" ::: "memory")
; #define WAIT_L(n) asm volatile("s_waitcnt lgkmcnt(" #n ")" ::: "memory")
; #define BAR __builtin_amdgcn_s_barrier()
; #define SCHED __builtin_amdgcn_sched_barrier(0)
; DEV void gemm_core(const u16* __restrict__ A, int lda, const u16* __restrict__ Bt, int ldb, int K,
;                    int brow, int bcol, f32x4 (&acc)[2][2][4][2]) {
;     ...
;     BAR; WAIT_L(0); MMA(1, 0, At, B0); BAR; SCHED;
;     STAGE(SB(1, 1), Bt, ldb, bcol + HALF, t + 3);
;     WAIT_V(6); BAR; MMA(1, 1, At, B1); BAR;
;   }
;   { LDB(B0, 0, 0); LDA(At, 0, 0); STAGE(SA(1, 1), A, lda, brow + HALF, nt - 1);
;     BAR; WAIT_L(0); MMA(0, 0, At, B0); BAR;
;     LDB(B1, 0, 1); BAR; WAIT_L(0); MMA(0, 1, At, B1); BAR;
	s_waitcnt lgkmcnt(0)
	v_mfma_f32_16x16x32_bf16 v[66:69], v[162:165], v[200:203], v[66:69]
	v_mfma_f32_16x16x32_bf16 v[62:65], v[170:173], v[200:203], v[62:65]
	v_mfma_f32_16x16x32_bf16 v[58:61], v[162:165], v[208:211], v[58:61]
	v_mfma_f32_16x16x32_bf16 v[54:57], v[170:173], v[208:211], v[54:57]
	v_mfma_f32_16x16x32_bf16 v[50:53], v[162:165], v[216:219], v[50:53]
	v_mfma_f32_16x16x32_bf16 v[46:49], v[170:173], v[216:219], v[46:49]
	v_mfma_f32_16x16x32_bf16 v[42:45], v[162:165], v[224:227], v[42:45]
	v_mfma_f32_16x16x32_bf16 v[38:41], v[170:173], v[224:227], v[38:41]
	v_mfma_f32_16x16x32_bf16 v[66:69], v[166:169], v[204:207], v[66:69]
	v_mfma_f32_16x16x32_bf16 v[62:65], v[174:177], v[204:207], v[62:65]
	v_mfma_f32_16x16x32_bf16 v[58:61], v[166:169], v[212:215], v[58:61]
	v_mfma_f32_16x16x32_bf16 v[54:57], v[174:177], v[212:215], v[54:57]
	v_mfma_f32_16x16x32_bf16 v[50:53], v[166:169], v[220:223], v[50:53]
	v_mfma_f32_16x16x32_bf16 v[46:49], v[174:177], v[220:223], v[46:49]
	v_mfma_f32_16x16x32_bf16 v[42:45], v[166:169], v[228:231], v[42:45]
	v_mfma_f32_16x16x32_bf16 v[38:41], v[174:177], v[228:231], v[38:41]
	v_add_u32_e32 v157, 0x80, v157
	v_add_u32_e32 v156, 0x80, v156
	s_add_i32 m0, s38, 0x1c000
	s_barrier
	global_load_lds_dwordx4 v155, s[8:9]
	s_add_i32 m0, s38, 0x1e000
	s_nop 0
	global_load_lds_dwordx4 v154, s[8:9]
	s_waitcnt vmcnt(6)
	s_barrier
	v_mfma_f32_16x16x32_bf16 v[34:37], v[232:235], v[200:203], v[34:37]
	v_mfma_f32_16x16x32_bf16 v[30:33], v[240:243], v[200:203], v[30:33]
	v_mfma_f32_16x16x32_bf16 v[26:29], v[232:235], v[208:211], v[26:29]
	v_mfma_f32_16x16x32_bf16 v[22:25], v[240:243], v[208:211], v[22:25]
	v_mfma_f32_16x16x32_bf16 v[18:21], v[232:235], v[216:219], v[18:21]
	v_mfma_f32_16x16x32_bf16 v[14:17], v[240:243], v[216:219], v[14:17]
	v_mfma_f32_16x16x32_bf16 v[10:13], v[232:235], v[224:227], v[10:13]
	v_mfma_f32_16x16x32_bf16 v[6:9], v[240:243], v[224:227], v[6:9]
	v_mfma_f32_16x16x32_bf16 v[34:37], v[236:239], v[204:207], v[34:37]
	v_mfma_f32_16x16x32_bf16 v[30:33], v[244:247], v[204:207], v[30:33]
	v_mfma_f32_16x16x32_bf16 v[26:29], v[236:239], v[212:215], v[26:29]
	v_mfma_f32_16x16x32_bf16 v[22:25], v[244:247], v[212:215], v[22:25]
	v_mfma_f32_16x16x32_bf16 v[18:21], v[236:239], v[220:223], v[18:21]
	v_mfma_f32_16x16x32_bf16 v[14:17], v[244:247], v[220:223], v[14:17]
	v_mfma_f32_16x16x32_bf16 v[10:13], v[236:239], v[228:231], v[10:13]
	v_mfma_f32_16x16x32_bf16 v[6:9], v[244:247], v[228:231], v[6:9]
	v_add_u32_e32 v155, 0x80, v155
	v_add_u32_e32 v154, 0x80, v154
	s_add_i32 m0, s38, 0xc000
	s_cmp_lt_i32 s36, s11
	s_barrier
	s_cbranch_scc1 .LBB0_191
	s_lshl_b32 s8, s13, 7
	v_add_u32_e32 v190, 16, v182
	s_add_i32 s10, s10, s8
	v_add_u32_e32 v4, 0x10000, v190
	s_and_b32 s8, s12, 0x1fc0
	ds_read_b128 v[130:133], v4
	ds_read_b128 v[134:137], v4 offset:1024
	ds_read_b128 v[150:153], v4 offset:2048
	ds_read_b128 v[154:157], v4 offset:3072
	s_add_i32 s8, s8, s10
	v_or_b32_e32 v4, 0xffffffc0, v142
	v_add_u32_e32 v140, s8, v4
	v_add_u32_e32 v4, v140, v149
	v_readfirstlane_b32 s8, v160
	v_lshl_add_u64 v[138:139], v[4:5], 1, s[6:7]
	s_mov_b32 m0, s8
	v_add_u32_e32 v4, v140, v141
	global_load_lds_dwordx4 v[138:139], off
	v_lshl_add_u64 v[138:139], v[4:5], 1, s[6:7]
	v_readfirstlane_b32 s6, v161
	s_mov_b32 m0, s6
	s_nop 0
	global_load_lds_dwordx4 v[138:139], off
	ds_read_b128 v[138:141], v197
	ds_read_b128 v[158:161], v197 offset:1024
	ds_read_b128 v[162:165], v197 offset:2048
	ds_read_b128 v[166:169], v197 offset:3072
	ds_read_b128 v[170:173], v197 offset:4096
	ds_read_b128 v[174:177], v197 offset:5120
	ds_read_b128 v[200:203], v197 offset:6144
	ds_read_b128 v[204:207], v197 offset:7168
	s_barrier
	s_waitcnt lgkmcnt(0)
	s_setprio 1
	s_waitcnt lgkmcnt(0)
	v_mfma_f32_16x16x32_bf16 v[0:3], v[130:133], v[138:141], v[0:3]
	v_mfma_f32_16x16x32_bf16 v[126:129], v[150:153], v[138:141], v[126:129]
	v_mfma_f32_16x16x32_bf16 v[122:125], v[130:133], v[162:165], v[122:125]
	v_mfma_f32_16x16x32_bf16 v[118:121], v[150:153], v[162:165], v[118:121]
	v_mfma_f32_16x16x32_bf16 v[114:117], v[130:133], v[170:173], v[114:117]
	v_mfma_f32_16x16x32_bf16 v[110:113], v[150:153], v[170:173], v[110:113]
	v_mfma_f32_16x16x32_bf16 v[106:109], v[130:133], v[200:203], v[106:109]
	v_mfma_f32_16x16x32_bf16 v[102:105], v[150:153], v[200:203], v[102:105]
	v_mfma_f32_16x16x32_bf16 v[0:3], v[134:137], v[158:161], v[0:3]
	v_mfma_f32_16x16x32_bf16 v[126:129], v[154:157], v[158:161], v[126:129]
	v_mfma_f32_16x16x32_bf16 v[122:125], v[134:137], v[166:169], v[122:125]
	v_mfma_f32_16x16x32_bf16 v[118:121], v[154:157], v[166:169], v[118:121]
	v_mfma_f32_16x16x32_bf16 v[114:117], v[134:137], v[174:177], v[114:117]
	v_mfma_f32_16x16x32_bf16 v[110:113], v[154:157], v[174:177], v[110:113]
	v_mfma_f32_16x16x32_bf16 v[106:109], v[134:137], v[204:207], v[106:109]
	v_mfma_f32_16x16x32_bf16 v[102:105], v[154:157], v[204:207], v[102:105]
	s_setprio 0
	v_add_u32_e32 v4, 0x14000, v190
	s_barrier
	ds_read_b128 v[208:211], v4
	ds_read_b128 v[212:215], v4 offset:1024
	ds_read_b128 v[216:219], v4 offset:2048
	ds_read_b128 v[220:223], v4 offset:3072
	s_barrier
; #define LDA(dst, b, h) for (int m = 0; m < 4; ++m) for (int k = 0; k < 2; ++k) \
;     dst[m][k] = *reinterpret_cast<const bf16x8*>((char*)SA(b, h) + aoff + m * 2048 + k * 1024)
; #define LDB(dst, b, h) for (int n = 0; n < 2; ++n) for (int k = 0; k < 2; ++k) \
;     dst[n][k] = *reinterpret_cast<const bf16x8*>((char*)SB(b, h) + boff + n * 2048 + k * 1024)
; #define MMA(ai, bj, At, Bt) do { __builtin_amdgcn_s_setprio(1); \
;     for (int m = 0; m < 4; ++m) for (int n = 0; n < 2; ++n) for (int k = 0; k < 2; ++k) \
;       acc[ai][bj][m][n] = __builtin_amdgcn_mfma_f32_16x16x32_bf16(Bt[n][k], At[m][k], acc[ai][bj][m][n], 0, 0, 0); \
;     __builtin_amdgcn_s_setprio(0); } while (0)
; #define WAIT_V(n) asm volatile("s_waitcnt vmcnt(" #n ")" ::: "memory")
; #define WAIT_L(n) asm volatile("s_waitcnt lgkmcnt(" #n ")" ::: "memory")
; #define BAR __builtin_amdgcn_s_barrier()
; DEV void gemm_core(const u16* __restrict__ A, int lda, const u16* __restrict__ Bt, int ldb, int K,
;                    int brow, int bcol, f32x4 (&acc)[2][2][4][2]) {
;     ...
;     LDB(B1, 0, 1); BAR; WAIT_L(0); MMA(0, 1, At, B1); BAR;
;     LDA(At, 0, 1); WAIT_V(4); BAR; WAIT_L(0); MMA(1, 0, At, B0); MMA(1, 1, At, B1); BAR; }
;   { LDB(B0, 1, 0); LDA(At, 1, 0); WAIT_V(2); BAR; WAIT_L(0); MMA(0, 0, At, B0); BAR;
	s_waitcnt lgkmcnt(0)
	s_setprio 1
	s_waitcnt lgkmcnt(0)
	v_mfma_f32_16x16x32_bf16 v[98:101], v[208:211], v[138:141], v[98:101]
	v_mfma_f32_16x16x32_bf16 v[94:97], v[216:219], v[138:141], v[94:97]
	v_mfma_f32_16x16x32_bf16 v[90:93], v[208:211], v[162:165], v[90:93]
	v_mfma_f32_16x16x32_bf16 v[86:89], v[216:219], v[162:165], v[86:89]
	v_mfma_f32_16x16x32_bf16 v[82:85], v[208:211], v[170:173], v[82:85]
	v_mfma_f32_16x16x32_bf16 v[78:81], v[216:219], v[170:173], v[78:81]
	v_mfma_f32_16x16x32_bf16 v[74:77], v[208:211], v[200:203], v[74:77]
	v_mfma_f32_16x16x32_bf16 v[70:73], v[216:219], v[200:203], v[70:73]
	v_mfma_f32_16x16x32_bf16 v[98:101], v[212:215], v[158:161], v[98:101]
	v_mfma_f32_16x16x32_bf16 v[94:97], v[220:223], v[158:161], v[94:97]
	v_mfma_f32_16x16x32_bf16 v[90:93], v[212:215], v[166:169], v[90:93]
	v_mfma_f32_16x16x32_bf16 v[86:89], v[220:223], v[166:169], v[86:89]
	v_mfma_f32_16x16x32_bf16 v[82:85], v[212:215], v[174:177], v[82:85]
	v_mfma_f32_16x16x32_bf16 v[78:81], v[220:223], v[174:177], v[78:81]
	v_mfma_f32_16x16x32_bf16 v[74:77], v[212:215], v[204:207], v[74:77]
	v_mfma_f32_16x16x32_bf16 v[70:73], v[220:223], v[204:207], v[70:73]
	s_setprio 0
	s_barrier
	ds_read_b128 v[138:141], v197 offset:16384
	ds_read_b128 v[158:161], v197 offset:17408
	ds_read_b128 v[162:165], v197 offset:18432
	ds_read_b128 v[166:169], v197 offset:19456
	ds_read_b128 v[170:173], v197 offset:20480
	ds_read_b128 v[174:177], v197 offset:21504
	ds_read_b128 v[200:203], v197 offset:22528
	ds_read_b128 v[204:207], v197 offset:23552
	s_waitcnt vmcnt(4)
	s_barrier
	s_waitcnt lgkmcnt(0)
	s_setprio 1
	s_waitcnt lgkmcnt(0)
	v_mfma_f32_16x16x32_bf16 v[66:69], v[130:133], v[138:141], v[66:69]
	v_mfma_f32_16x16x32_bf16 v[62:65], v[150:153], v[138:141], v[62:65]
	v_mfma_f32_16x16x32_bf16 v[58:61], v[130:133], v[162:165], v[58:61]
	v_mfma_f32_16x16x32_bf16 v[54:57], v[150:153], v[162:165], v[54:57]
	v_mfma_f32_16x16x32_bf16 v[50:53], v[130:133], v[170:173], v[50:53]
	v_mfma_f32_16x16x32_bf16 v[46:49], v[150:153], v[170:173], v[46:49]
	v_mfma_f32_16x16x32_bf16 v[42:45], v[130:133], v[200:203], v[42:45]
	v_mfma_f32_16x16x32_bf16 v[38:41], v[150:153], v[200:203], v[38:41]
	v_mfma_f32_16x16x32_bf16 v[66:69], v[134:137], v[158:161], v[66:69]
	v_mfma_f32_16x16x32_bf16 v[62:65], v[154:157], v[158:161], v[62:65]
	v_mfma_f32_16x16x32_bf16 v[58:61], v[134:137], v[166:169], v[58:61]
	v_mfma_f32_16x16x32_bf16 v[54:57], v[154:157], v[166:169], v[54:57]
	v_mfma_f32_16x16x32_bf16 v[50:53], v[134:137], v[174:177], v[50:53]
	v_mfma_f32_16x16x32_bf16 v[46:49], v[154:157], v[174:177], v[46:49]
	v_mfma_f32_16x16x32_bf16 v[42:45], v[134:137], v[204:207], v[42:45]
	v_mfma_f32_16x16x32_bf16 v[38:41], v[154:157], v[204:207], v[38:41]
	s_setprio 0
	s_setprio 1
	v_mfma_f32_16x16x32_bf16 v[34:37], v[208:211], v[138:141], v[34:37]
	v_mfma_f32_16x16x32_bf16 v[30:33], v[216:219], v[138:141], v[30:33]
	v_mfma_f32_16x16x32_bf16 v[26:29], v[208:211], v[162:165], v[26:29]
	v_mfma_f32_16x16x32_bf16 v[22:25], v[216:219], v[162:165], v[22:25]
	v_mfma_f32_16x16x32_bf16 v[18:21], v[208:211], v[170:173], v[18:21]
	v_mfma_f32_16x16x32_bf16 v[14:17], v[216:219], v[170:173], v[14:17]
	v_mfma_f32_16x16x32_bf16 v[10:13], v[208:211], v[200:203], v[10:13]
	v_mfma_f32_16x16x32_bf16 v[6:9], v[216:219], v[200:203], v[6:9]
	v_mfma_f32_16x16x32_bf16 v[34:37], v[212:215], v[158:161], v[34:37]
	v_mfma_f32_16x16x32_bf16 v[30:33], v[220:223], v[158:161], v[30:33]
	v_mfma_f32_16x16x32_bf16 v[26:29], v[212:215], v[166:169], v[26:29]
	v_mfma_f32_16x16x32_bf16 v[22:25], v[220:223], v[166:169], v[22:25]
	v_mfma_f32_16x16x32_bf16 v[18:21], v[212:215], v[174:177], v[18:21]
	v_mfma_f32_16x16x32_bf16 v[14:17], v[220:223], v[174:177], v[14:17]
	v_mfma_f32_16x16x32_bf16 v[10:13], v[212:215], v[204:207], v[10:13]
	v_mfma_f32_16x16x32_bf16 v[6:9], v[220:223], v[204:207], v[6:9]
	s_setprio 0
	v_add_u32_e32 v4, 0x18000, v190
	s_barrier
	ds_read_b128 v[130:133], v4
	ds_read_b128 v[134:137], v4 offset:1024
	ds_read_b128 v[138:141], v4 offset:2048
	ds_read_b128 v[148:151], v4 offset:3072
	ds_read_b128 v[152:155], v197 offset:32768
	ds_read_b128 v[156:159], v197 offset:33792
	ds_read_b128 v[160:163], v197 offset:34816
	ds_read_b128 v[164:167], v197 offset:35840
	ds_read_b128 v[168:171], v197 offset:36864
	ds_read_b128 v[172:175], v197 offset:37888
	ds_read_b128 v[200:203], v197 offset:38912
	ds_read_b128 v[204:207], v197 offset:39936
	s_waitcnt vmcnt(2)
	s_barrier
; #define LDA(dst, b, h) for (int m = 0; m < 4; ++m) for (int k = 0; k < 2; ++k) \
;     dst[m][k] = *reinterpret_cast<const bf16x8*>((char*)SA(b, h) + aoff + m * 2048 + k * 1024)
; #define LDB(dst, b, h) for (int n = 0; n < 2; ++n) for (int k = 0; k < 2; ++k) \
;     dst[n][k] = *reinterpret_cast<const bf16x8*>((char*)SB(b, h) + boff + n * 2048 + k * 1024)
; #define MMA(ai, bj, At, Bt) do { __builtin_amdgcn_s_setprio(1); \
;     for (int m = 0; m < 4; ++m) for (int n = 0; n < 2; ++n) for (int k = 0; k < 2; ++k) \
;       acc[ai][bj][m][n] = __builtin_amdgcn_mfma_f32_16x16x32_bf16(Bt[n][k], At[m][k], acc[ai][bj][m][n], 0, 0, 0); \
;     __builtin_amdgcn_s_setprio(0); } while (0)
; #define WAIT_V(n) asm volatile("s_waitcnt vmcnt(" #n ")" ::: "memory")
; #define WAIT_L(n) asm volatile("s_waitcnt lgkmcnt(" #n ")" ::: "memory")
; #define BAR __builtin_amdgcn_s_barrier()
; DEV void gemm_core(const u16* __restrict__ A, int lda, const u16* __restrict__ Bt, int ldb, int K,
;                    int brow, int bcol, f32x4 (&acc)[2][2][4][2]) {
;     ...
;   { LDB(B0, 1, 0); LDA(At, 1, 0); WAIT_V(2); BAR; WAIT_L(0); MMA(0, 0, At, B0); BAR;
;     LDB(B1, 1, 1); WAIT_V(0); BAR; WAIT_L(0); MMA(0, 1, At, B1); BAR;
;     LDA(At, 1, 1); BAR; WAIT_L(0); MMA(1, 0, At, B0); MMA(1, 1, At, B1); BAR; }
;   if (wr == 0) BAR;
	s_waitcnt lgkmcnt(0)
	s_setprio 1
	s_waitcnt lgkmcnt(0)
	v_mfma_f32_16x16x32_bf16 v[0:3], v[130:133], v[152:155], v[0:3]
	v_mfma_f32_16x16x32_bf16 v[126:129], v[138:141], v[152:155], v[126:129]
	v_mfma_f32_16x16x32_bf16 v[122:125], v[130:133], v[160:163], v[122:125]
	v_mfma_f32_16x16x32_bf16 v[118:121], v[138:141], v[160:163], v[118:121]
	v_mfma_f32_16x16x32_bf16 v[114:117], v[130:133], v[168:171], v[114:117]
	v_mfma_f32_16x16x32_bf16 v[110:113], v[138:141], v[168:171], v[110:113]
	v_mfma_f32_16x16x32_bf16 v[106:109], v[130:133], v[200:203], v[106:109]
	v_mfma_f32_16x16x32_bf16 v[102:105], v[138:141], v[200:203], v[102:105]
	v_mfma_f32_16x16x32_bf16 v[0:3], v[134:137], v[156:159], v[0:3]
	v_mfma_f32_16x16x32_bf16 v[126:129], v[148:151], v[156:159], v[126:129]
	v_mfma_f32_16x16x32_bf16 v[122:125], v[134:137], v[164:167], v[122:125]
	v_mfma_f32_16x16x32_bf16 v[118:121], v[148:151], v[164:167], v[118:121]
	v_mfma_f32_16x16x32_bf16 v[114:117], v[134:137], v[172:175], v[114:117]
	v_mfma_f32_16x16x32_bf16 v[110:113], v[148:151], v[172:175], v[110:113]
	v_mfma_f32_16x16x32_bf16 v[106:109], v[134:137], v[204:207], v[106:109]
	v_mfma_f32_16x16x32_bf16 v[102:105], v[148:151], v[204:207], v[102:105]
	s_setprio 0
	v_add_u32_e32 v4, 0x1c000, v190
	s_barrier
	ds_read_b128 v[208:211], v4
	ds_read_b128 v[212:215], v4 offset:1024
	ds_read_b128 v[216:219], v4 offset:2048
	ds_read_b128 v[220:223], v4 offset:3072
	s_waitcnt vmcnt(0)
	s_barrier
	s_waitcnt lgkmcnt(0)
	s_setprio 1
	s_waitcnt lgkmcnt(0)
	v_mfma_f32_16x16x32_bf16 v[98:101], v[208:211], v[152:155], v[98:101]
	v_mfma_f32_16x16x32_bf16 v[94:97], v[216:219], v[152:155], v[94:97]
	v_mfma_f32_16x16x32_bf16 v[90:93], v[208:211], v[160:163], v[90:93]
	v_mfma_f32_16x16x32_bf16 v[86:89], v[216:219], v[160:163], v[86:89]
	v_mfma_f32_16x16x32_bf16 v[82:85], v[208:211], v[168:171], v[82:85]
	v_mfma_f32_16x16x32_bf16 v[78:81], v[216:219], v[168:171], v[78:81]
	v_mfma_f32_16x16x32_bf16 v[74:77], v[208:211], v[200:203], v[74:77]
	v_mfma_f32_16x16x32_bf16 v[70:73], v[216:219], v[200:203], v[70:73]
	v_mfma_f32_16x16x32_bf16 v[98:101], v[212:215], v[156:159], v[98:101]
	v_mfma_f32_16x16x32_bf16 v[94:97], v[220:223], v[156:159], v[94:97]
	v_mfma_f32_16x16x32_bf16 v[90:93], v[212:215], v[164:167], v[90:93]
	v_mfma_f32_16x16x32_bf16 v[86:89], v[220:223], v[164:167], v[86:89]
	v_mfma_f32_16x16x32_bf16 v[82:85], v[212:215], v[172:175], v[82:85]
	v_mfma_f32_16x16x32_bf16 v[78:81], v[220:223], v[172:175], v[78:81]
	v_mfma_f32_16x16x32_bf16 v[74:77], v[212:215], v[204:207], v[74:77]
	v_mfma_f32_16x16x32_bf16 v[70:73], v[220:223], v[204:207], v[70:73]
	s_setprio 0
	s_barrier
	ds_read_b128 v[152:155], v197 offset:49152
	ds_read_b128 v[156:159], v197 offset:50176
	ds_read_b128 v[160:163], v197 offset:51200
	ds_read_b128 v[164:167], v197 offset:52224
	ds_read_b128 v[168:171], v197 offset:53248
	ds_read_b128 v[172:175], v197 offset:54272
	ds_read_b128 v[200:203], v197 offset:55296
	ds_read_b128 v[204:207], v197 offset:56320
	s_barrier
	s_waitcnt lgkmcnt(0)
	s_setprio 1
	s_waitcnt lgkmcnt(0)
	v_mfma_f32_16x16x32_bf16 v[66:69], v[130:133], v[152:155], v[66:69]
	v_mfma_f32_16x16x32_bf16 v[62:65], v[138:141], v[152:155], v[62:65]
	v_mfma_f32_16x16x32_bf16 v[58:61], v[130:133], v[160:163], v[58:61]
	v_mfma_f32_16x16x32_bf16 v[54:57], v[138:141], v[160:163], v[54:57]
	v_mfma_f32_16x16x32_bf16 v[50:53], v[130:133], v[168:171], v[50:53]
	v_mfma_f32_16x16x32_bf16 v[46:49], v[138:141], v[168:171], v[46:49]
	v_mfma_f32_16x16x32_bf16 v[42:45], v[130:133], v[200:203], v[42:45]
	v_mfma_f32_16x16x32_bf16 v[38:41], v[138:141], v[200:203], v[38:41]
	v_mfma_f32_16x16x32_bf16 v[66:69], v[134:137], v[156:159], v[66:69]
	v_mfma_f32_16x16x32_bf16 v[62:65], v[148:151], v[156:159], v[62:65]
	v_mfma_f32_16x16x32_bf16 v[58:61], v[134:137], v[164:167], v[58:61]
	v_mfma_f32_16x16x32_bf16 v[54:57], v[148:151], v[164:167], v[54:57]
	v_mfma_f32_16x16x32_bf16 v[50:53], v[134:137], v[172:175], v[50:53]
	v_mfma_f32_16x16x32_bf16 v[46:49], v[148:151], v[172:175], v[46:49]
	v_mfma_f32_16x16x32_bf16 v[42:45], v[134:137], v[204:207], v[42:45]
	v_mfma_f32_16x16x32_bf16 v[38:41], v[148:151], v[204:207], v[38:41]
	s_setprio 0
	s_setprio 1
	v_mfma_f32_16x16x32_bf16 v[34:37], v[208:211], v[152:155], v[34:37]
	v_mfma_f32_16x16x32_bf16 v[30:33], v[216:219], v[152:155], v[30:33]
	v_mfma_f32_16x16x32_bf16 v[26:29], v[208:211], v[160:163], v[26:29]
	v_mfma_f32_16x16x32_bf16 v[22:25], v[216:219], v[160:163], v[22:25]
	v_mfma_f32_16x16x32_bf16 v[18:21], v[208:211], v[168:171], v[18:21]
	v_mfma_f32_16x16x32_bf16 v[14:17], v[216:219], v[168:171], v[14:17]
	v_mfma_f32_16x16x32_bf16 v[10:13], v[208:211], v[200:203], v[10:13]
	v_mfma_f32_16x16x32_bf16 v[6:9], v[216:219], v[200:203], v[6:9]
	v_mfma_f32_16x16x32_bf16 v[34:37], v[212:215], v[156:159], v[34:37]
	v_mfma_f32_16x16x32_bf16 v[30:33], v[220:223], v[156:159], v[30:33]
	v_mfma_f32_16x16x32_bf16 v[26:29], v[212:215], v[164:167], v[26:29]
	v_mfma_f32_16x16x32_bf16 v[22:25], v[220:223], v[164:167], v[22:25]
	v_mfma_f32_16x16x32_bf16 v[18:21], v[212:215], v[172:175], v[18:21]
	v_mfma_f32_16x16x32_bf16 v[14:17], v[220:223], v[172:175], v[14:17]
	v_mfma_f32_16x16x32_bf16 v[10:13], v[212:215], v[204:207], v[10:13]
	v_mfma_f32_16x16x32_bf16 v[6:9], v[220:223], v[204:207], v[6:9]
	s_setprio 0
	s_barrier
	s_mov_b64 s[6:7], exec
	v_readlane_b32 s8, v254, 51
	v_readlane_b32 s9, v254, 52
	s_and_b64 s[8:9], s[6:7], s[8:9]
	s_mov_b64 exec, s[8:9]
	s_cbranch_execz .LBB0_194
	s_barrier
